# down-GEMM epilogue: 16 residual loads fetched in two batches instead of load+vmcnt(0) per block (on E1+E3+E25)
# speedup vs baseline: 1.0006x; 1.0006x over previous
.LBB0_1375:
	s_cmp_lg_u32 s94, -2
	s_cselect_b64 s[80:81], -1, 0
	s_cmp_eq_u32 s94, -2
	s_cbranch_scc1 .LBB0_1476
	s_cmp_lt_i32 s94, 0
	s_mov_b64 s[40:41], -1
	s_cbranch_scc0 .LBB0_1474
	v_lshl_add_u32 v170, s24, 8, v1
	v_ashrrev_i32_e32 v171, 31, v170
	s_waitcnt lgkmcnt(0)
	v_lshl_or_b32 v116, s22, 8, v151
	v_lshlrev_b64 v[136:137], 13, v[170:171]
	v_ashrrev_i32_e32 v117, 31, v116
	v_lshl_add_u64 v[136:137], s[46:47], 0, v[136:137]
	v_lshl_add_u64 v[174:175], v[116:117], 1, v[136:137]
	s_mov_b64 s[100:101], 0x20000
	global_load_dwordx4 v[184:187], v[174:175], off
	global_load_dwordx4 v[188:191], v[174:175], off offset:256
	v_lshl_add_u64 v[196:197], v[174:175], 0, s[100:101]
	global_load_dwordx4 v[192:195], v[196:197], off
	global_load_dwordx4 v[210:213], v[196:197], off offset:256
	v_lshl_add_u64 v[196:197], v[196:197], 0, s[100:101]
	global_load_dwordx4 v[214:217], v[196:197], off
	global_load_dwordx4 v[218:221], v[196:197], off offset:256
	v_lshl_add_u64 v[196:197], v[196:197], 0, s[100:101]
	global_load_dwordx4 v[222:225], v[196:197], off
	global_load_dwordx4 v[226:229], v[196:197], off offset:256
	s_mov_b64 s[100:101], 0x100000
	v_lshl_add_u64 v[196:197], v[174:175], 0, s[100:101]
	global_load_dwordx4 v[236:239], v[196:197], off
	global_load_dwordx4 v[240:243], v[196:197], off offset:256
	v_readlane_b32 s8, v254, 48
	v_readlane_b32 s9, v254, 49
	v_lshlrev_b64 v[172:173], 12, v[170:171]
	s_mov_b64 s[82:83], -1
	v_cndmask_b32_e64 v114, 0, 1, s[8:9]
	v_cmp_ne_u32_e64 s[40:41], 1, v114
	s_andn2_b64 vcc, exec, s[8:9]
	v_lshl_add_u64 v[172:173], v[172:173], 1, s[50:51]
	s_waitcnt vmcnt(0)
	s_nop 1
	v_mov_b32_e32 v136, v184
	v_mov_b32_e32 v137, v185
	v_mov_b32_e32 v138, v186
	v_mov_b32_e32 v139, v187
	v_lshlrev_b32_e32 v140, 16, v136
	v_and_b32_e32 v141, 0xffff0000, v136
	v_lshlrev_b32_e32 v136, 16, v137
	v_and_b32_e32 v137, 0xffff0000, v137
	v_lshlrev_b32_e32 v176, 16, v138
	v_and_b32_e32 v177, 0xffff0000, v138
	v_lshlrev_b32_e32 v142, 16, v139
	v_and_b32_e32 v143, 0xffff0000, v139
	v_pk_add_f32 v[138:139], v[134:135], v[136:137]
	v_pk_add_f32 v[136:137], v[132:133], v[140:141]
	v_pk_add_f32 v[142:143], v[130:131], v[142:143]
	v_pk_add_f32 v[140:141], v[128:129], v[176:177]
	s_cbranch_vccnz .LBB0_1379
	v_cvt_pk_bf16_f32 v176, v136, v137
	v_cvt_pk_bf16_f32 v177, v138, v139
	v_cvt_pk_bf16_f32 v178, v140, v141
	v_cvt_pk_bf16_f32 v179, v142, v143
	v_lshl_add_u64 v[180:181], v[116:117], 1, v[172:173]
	global_store_dwordx4 v[180:181], v[176:179], off
	v_mov_b32_e32 v180, v139
	v_mov_b32_e32 v181, v143
	v_mov_b32_e32 v178, v137
	v_mov_b32_e32 v179, v141
	v_mov_b32_e32 v176, v136
	v_mov_b32_e32 v177, v140
	v_pk_mul_f32 v[178:179], v[178:179], v[178:179]
	v_pk_mul_f32 v[180:181], v[180:181], v[180:181]
	v_pk_fma_f32 v[176:177], v[176:177], v[176:177], v[178:179]
	v_mov_b32_e32 v178, v138
	v_mov_b32_e32 v179, v142
	v_pk_fma_f32 v[178:179], v[178:179], v[178:179], v[180:181]
	s_mov_b64 s[82:83], 0
	v_pk_add_f32 v[176:177], v[176:177], v[178:179]
	s_nop 0
	v_add_f32_e32 v114, v176, v177

.LBB0_1381:
	s_and_b64 vcc, exec, s[40:41]
	s_mov_b64 s[82:83], -1
	s_nop 1
	v_mov_b32_e32 v136, v188
	v_mov_b32_e32 v137, v189
	v_mov_b32_e32 v138, v190
	v_mov_b32_e32 v139, v191
	v_lshlrev_b32_e32 v140, 16, v136
	v_and_b32_e32 v141, 0xffff0000, v136
	v_lshlrev_b32_e32 v136, 16, v137
	v_and_b32_e32 v137, 0xffff0000, v137
	v_lshlrev_b32_e32 v174, 16, v138
	v_and_b32_e32 v175, 0xffff0000, v138
	v_lshlrev_b32_e32 v142, 16, v139
	v_and_b32_e32 v143, 0xffff0000, v139
	v_pk_add_f32 v[138:139], v[96:97], v[136:137]
	v_pk_add_f32 v[136:137], v[94:95], v[140:141]
	v_pk_add_f32 v[142:143], v[92:93], v[142:143]
	v_pk_add_f32 v[140:141], v[90:91], v[174:175]
	s_cbranch_vccz .LBB0_1384
	s_andn2_b64 vcc, exec, s[82:83]
	s_cbranch_vccz .LBB0_1385

.LBB0_1389:
	v_or_b32_e32 v172, 16, v170
	v_ashrrev_i32_e32 v173, 31, v172
	s_waitcnt lgkmcnt(0)
	v_lshlrev_b64 v[136:137], 13, v[172:173]
	v_lshl_add_u64 v[136:137], s[46:47], 0, v[136:137]
	v_lshl_add_u64 v[178:179], v[116:117], 1, v[136:137]
	v_lshlrev_b64 v[174:175], 12, v[172:173]
	s_mov_b64 s[82:83], -1
	s_and_b64 vcc, exec, s[40:41]
	v_lshl_add_u64 v[174:175], v[174:175], 1, s[50:51]
	s_nop 1
	v_mov_b32_e32 v136, v192
	v_mov_b32_e32 v137, v193
	v_mov_b32_e32 v138, v194
	v_mov_b32_e32 v139, v195
	v_lshlrev_b32_e32 v140, 16, v136
	v_and_b32_e32 v141, 0xffff0000, v136
	v_lshlrev_b32_e32 v136, 16, v137
	v_and_b32_e32 v137, 0xffff0000, v137
	v_lshlrev_b32_e32 v176, 16, v138
	v_and_b32_e32 v177, 0xffff0000, v138
	v_lshlrev_b32_e32 v142, 16, v139
	v_and_b32_e32 v143, 0xffff0000, v139
	v_pk_add_f32 v[138:139], v[126:127], v[136:137]
	v_pk_add_f32 v[136:137], v[124:125], v[140:141]
	v_pk_add_f32 v[142:143], v[122:123], v[142:143]
	v_pk_add_f32 v[140:141], v[120:121], v[176:177]
	s_cbranch_vccnz .LBB0_1391
	v_cvt_pk_bf16_f32 v180, v136, v137
	v_cvt_pk_bf16_f32 v181, v138, v139
	v_lshl_add_u64 v[176:177], v[116:117], 1, v[174:175]
	v_cvt_pk_bf16_f32 v182, v140, v141
	v_cvt_pk_bf16_f32 v183, v142, v143
	global_store_dwordx4 v[176:177], v[180:183], off
	v_mov_b32_e32 v176, v136
	v_mov_b32_e32 v177, v140
	v_mov_b32_e32 v180, v137
	v_mov_b32_e32 v181, v141
	v_pk_mul_f32 v[180:181], v[180:181], v[180:181]
	v_mov_b32_e32 v182, v139
	v_mov_b32_e32 v183, v143
	v_pk_fma_f32 v[176:177], v[176:177], v[176:177], v[180:181]
	v_mov_b32_e32 v180, v138
	v_mov_b32_e32 v181, v142
	v_pk_mul_f32 v[182:183], v[182:183], v[182:183]
	s_mov_b64 s[82:83], 0
	v_pk_fma_f32 v[180:181], v[180:181], v[180:181], v[182:183]
	s_nop 0
	v_pk_add_f32 v[176:177], v[176:177], v[180:181]
	s_nop 0
	v_add_f32_e32 v114, v176, v177

.LBB0_1393:
	s_and_b64 vcc, exec, s[40:41]
	s_mov_b64 s[82:83], -1
	s_nop 1
	v_mov_b32_e32 v136, v210
	v_mov_b32_e32 v137, v211
	v_mov_b32_e32 v138, v212
	v_mov_b32_e32 v139, v213
	v_lshlrev_b32_e32 v140, 16, v136
	v_and_b32_e32 v141, 0xffff0000, v136
	v_lshlrev_b32_e32 v136, 16, v137
	v_and_b32_e32 v137, 0xffff0000, v137
	v_lshlrev_b32_e32 v178, 16, v138
	v_and_b32_e32 v179, 0xffff0000, v138
	v_lshlrev_b32_e32 v142, 16, v139
	v_and_b32_e32 v143, 0xffff0000, v139
	v_pk_add_f32 v[138:139], v[88:89], v[136:137]
	v_pk_add_f32 v[136:137], v[86:87], v[140:141]
	v_pk_add_f32 v[142:143], v[84:85], v[142:143]
	v_pk_add_f32 v[140:141], v[82:83], v[178:179]
	s_cbranch_vccz .LBB0_1396
	s_andn2_b64 vcc, exec, s[82:83]
	s_cbranch_vccz .LBB0_1397

.LBB0_1401:
	v_or_b32_e32 v172, 32, v170
	v_ashrrev_i32_e32 v173, 31, v172
	s_waitcnt lgkmcnt(0)
	v_lshlrev_b64 v[136:137], 13, v[172:173]
	v_lshl_add_u64 v[136:137], s[46:47], 0, v[136:137]
	v_lshl_add_u64 v[178:179], v[116:117], 1, v[136:137]
	v_lshlrev_b64 v[174:175], 12, v[172:173]
	s_mov_b64 s[82:83], -1
	s_and_b64 vcc, exec, s[40:41]
	v_lshl_add_u64 v[174:175], v[174:175], 1, s[50:51]
	s_nop 1
	v_mov_b32_e32 v136, v214
	v_mov_b32_e32 v137, v215
	v_mov_b32_e32 v138, v216
	v_mov_b32_e32 v139, v217
	v_lshlrev_b32_e32 v140, 16, v136
	v_and_b32_e32 v141, 0xffff0000, v136
	v_lshlrev_b32_e32 v136, 16, v137
	v_and_b32_e32 v137, 0xffff0000, v137
	v_lshlrev_b32_e32 v176, 16, v138
	v_and_b32_e32 v177, 0xffff0000, v138
	v_lshlrev_b32_e32 v142, 16, v139
	v_and_b32_e32 v143, 0xffff0000, v139
	v_pk_add_f32 v[138:139], v[112:113], v[136:137]
	v_pk_add_f32 v[136:137], v[110:111], v[140:141]
	v_pk_add_f32 v[142:143], v[108:109], v[142:143]
	v_pk_add_f32 v[140:141], v[106:107], v[176:177]
	s_cbranch_vccnz .LBB0_1403
	v_cvt_pk_bf16_f32 v180, v136, v137
	v_cvt_pk_bf16_f32 v181, v138, v139
	v_lshl_add_u64 v[176:177], v[116:117], 1, v[174:175]
	v_cvt_pk_bf16_f32 v182, v140, v141
	v_cvt_pk_bf16_f32 v183, v142, v143
	global_store_dwordx4 v[176:177], v[180:183], off
	v_mov_b32_e32 v176, v136
	v_mov_b32_e32 v177, v140
	v_mov_b32_e32 v180, v137
	v_mov_b32_e32 v181, v141
	v_pk_mul_f32 v[180:181], v[180:181], v[180:181]
	v_mov_b32_e32 v182, v139
	v_mov_b32_e32 v183, v143
	v_pk_fma_f32 v[176:177], v[176:177], v[176:177], v[180:181]
	v_mov_b32_e32 v180, v138
	v_mov_b32_e32 v181, v142
	v_pk_mul_f32 v[182:183], v[182:183], v[182:183]
	s_mov_b64 s[82:83], 0
	v_pk_fma_f32 v[180:181], v[180:181], v[180:181], v[182:183]
	s_nop 0
	v_pk_add_f32 v[176:177], v[176:177], v[180:181]
	s_nop 0
	v_add_f32_e32 v114, v176, v177

.LBB0_1405:
	s_and_b64 vcc, exec, s[40:41]
	s_mov_b64 s[82:83], -1
	s_nop 1
	v_mov_b32_e32 v136, v218
	v_mov_b32_e32 v137, v219
	v_mov_b32_e32 v138, v220
	v_mov_b32_e32 v139, v221
	v_lshlrev_b32_e32 v140, 16, v136
	v_and_b32_e32 v141, 0xffff0000, v136
	v_lshlrev_b32_e32 v136, 16, v137
	v_and_b32_e32 v137, 0xffff0000, v137
	v_lshlrev_b32_e32 v178, 16, v138
	v_and_b32_e32 v179, 0xffff0000, v138
	v_lshlrev_b32_e32 v142, 16, v139
	v_and_b32_e32 v143, 0xffff0000, v139
	v_pk_add_f32 v[138:139], v[80:81], v[136:137]
	v_pk_add_f32 v[136:137], v[78:79], v[140:141]
	v_pk_add_f32 v[142:143], v[76:77], v[142:143]
	v_pk_add_f32 v[140:141], v[74:75], v[178:179]
	s_cbranch_vccz .LBB0_1408
	s_andn2_b64 vcc, exec, s[82:83]
	s_cbranch_vccz .LBB0_1409

.LBB0_1413:
	v_or_b32_e32 v172, 48, v170
	v_ashrrev_i32_e32 v173, 31, v172
	s_waitcnt lgkmcnt(0)
	v_lshlrev_b64 v[136:137], 13, v[172:173]
	v_lshl_add_u64 v[136:137], s[46:47], 0, v[136:137]
	v_lshl_add_u64 v[178:179], v[116:117], 1, v[136:137]
	v_lshlrev_b64 v[174:175], 12, v[172:173]
	s_mov_b64 s[82:83], -1
	s_and_b64 vcc, exec, s[40:41]
	v_lshl_add_u64 v[174:175], v[174:175], 1, s[50:51]
	s_nop 1
	v_mov_b32_e32 v136, v222
	v_mov_b32_e32 v137, v223
	v_mov_b32_e32 v138, v224
	v_mov_b32_e32 v139, v225
	v_lshlrev_b32_e32 v140, 16, v136
	v_and_b32_e32 v141, 0xffff0000, v136
	v_lshlrev_b32_e32 v136, 16, v137
	v_and_b32_e32 v137, 0xffff0000, v137
	v_lshlrev_b32_e32 v176, 16, v138
	v_and_b32_e32 v177, 0xffff0000, v138
	v_lshlrev_b32_e32 v142, 16, v139
	v_and_b32_e32 v143, 0xffff0000, v139
	v_pk_add_f32 v[138:139], v[104:105], v[136:137]
	v_pk_add_f32 v[136:137], v[102:103], v[140:141]
	v_pk_add_f32 v[142:143], v[100:101], v[142:143]
	v_pk_add_f32 v[140:141], v[98:99], v[176:177]
	s_cbranch_vccnz .LBB0_1415
	v_cvt_pk_bf16_f32 v180, v136, v137
	v_cvt_pk_bf16_f32 v181, v138, v139
	v_lshl_add_u64 v[176:177], v[116:117], 1, v[174:175]
	v_cvt_pk_bf16_f32 v182, v140, v141
	v_cvt_pk_bf16_f32 v183, v142, v143
	global_store_dwordx4 v[176:177], v[180:183], off
	v_mov_b32_e32 v176, v136
	v_mov_b32_e32 v177, v140
	v_mov_b32_e32 v180, v137
	v_mov_b32_e32 v181, v141
	v_pk_mul_f32 v[180:181], v[180:181], v[180:181]
	v_mov_b32_e32 v182, v139
	v_mov_b32_e32 v183, v143
	v_pk_fma_f32 v[176:177], v[176:177], v[176:177], v[180:181]
	v_mov_b32_e32 v180, v138
	v_mov_b32_e32 v181, v142
	v_pk_mul_f32 v[182:183], v[182:183], v[182:183]
	s_mov_b64 s[82:83], 0
	v_pk_fma_f32 v[180:181], v[180:181], v[180:181], v[182:183]
	s_nop 0
	v_pk_add_f32 v[176:177], v[176:177], v[180:181]
	s_nop 0
	v_add_f32_e32 v114, v176, v177

.LBB0_1417:
	s_and_b64 vcc, exec, s[40:41]
	s_mov_b64 s[82:83], -1
	s_nop 1
	v_mov_b32_e32 v136, v226
	v_mov_b32_e32 v137, v227
	v_mov_b32_e32 v138, v228
	v_mov_b32_e32 v139, v229
	v_lshlrev_b32_e32 v140, 16, v136
	v_and_b32_e32 v141, 0xffff0000, v136
	v_lshlrev_b32_e32 v136, 16, v137
	v_and_b32_e32 v137, 0xffff0000, v137
	v_lshlrev_b32_e32 v178, 16, v138
	v_and_b32_e32 v179, 0xffff0000, v138
	v_lshlrev_b32_e32 v142, 16, v139
	v_and_b32_e32 v143, 0xffff0000, v139
	v_pk_add_f32 v[138:139], v[68:69], v[136:137]
	v_pk_add_f32 v[136:137], v[66:67], v[140:141]
	v_pk_add_f32 v[142:143], v[60:61], v[142:143]
	v_pk_add_f32 v[140:141], v[58:59], v[178:179]
	s_cbranch_vccz .LBB0_1420
	s_andn2_b64 vcc, exec, s[82:83]
	s_cbranch_vccz .LBB0_1421

.LBB0_1425:
	v_add_u32_e32 v172, 0x80, v170
	v_ashrrev_i32_e32 v173, 31, v172
	s_waitcnt lgkmcnt(0)
	v_lshlrev_b64 v[136:137], 13, v[172:173]
	v_lshl_add_u64 v[136:137], s[46:47], 0, v[136:137]
	v_lshl_add_u64 v[178:179], v[116:117], 1, v[136:137]
	v_lshlrev_b64 v[174:175], 12, v[172:173]
	s_mov_b64 s[82:83], -1
	s_and_b64 vcc, exec, s[40:41]
	v_lshl_add_u64 v[174:175], v[174:175], 1, s[50:51]
	s_nop 1
	v_mov_b32_e32 v136, v236
	v_mov_b32_e32 v137, v237
	v_mov_b32_e32 v138, v238
	v_mov_b32_e32 v139, v239
	v_lshlrev_b32_e32 v140, 16, v136
	v_and_b32_e32 v141, 0xffff0000, v136
	v_lshlrev_b32_e32 v136, 16, v137
	v_and_b32_e32 v137, 0xffff0000, v137
	v_lshlrev_b32_e32 v176, 16, v138
	v_and_b32_e32 v177, 0xffff0000, v138
	v_lshlrev_b32_e32 v142, 16, v139
	v_and_b32_e32 v143, 0xffff0000, v139
	v_pk_add_f32 v[138:139], v[72:73], v[136:137]
	v_pk_add_f32 v[136:137], v[70:71], v[140:141]
	v_pk_add_f32 v[142:143], v[64:65], v[142:143]
	v_pk_add_f32 v[140:141], v[62:63], v[176:177]
	s_cbranch_vccnz .LBB0_1427
	v_cvt_pk_bf16_f32 v180, v136, v137
	v_cvt_pk_bf16_f32 v181, v138, v139
	v_lshl_add_u64 v[176:177], v[116:117], 1, v[174:175]
	v_cvt_pk_bf16_f32 v182, v140, v141
	v_cvt_pk_bf16_f32 v183, v142, v143
	global_store_dwordx4 v[176:177], v[180:183], off
	v_mov_b32_e32 v176, v136
	v_mov_b32_e32 v177, v140
	v_mov_b32_e32 v180, v137
	v_mov_b32_e32 v181, v141
	v_pk_mul_f32 v[180:181], v[180:181], v[180:181]
	v_mov_b32_e32 v182, v139
	v_mov_b32_e32 v183, v143
	v_pk_fma_f32 v[176:177], v[176:177], v[176:177], v[180:181]
	v_mov_b32_e32 v180, v138
	v_mov_b32_e32 v181, v142
	v_pk_mul_f32 v[182:183], v[182:183], v[182:183]
	s_mov_b64 s[82:83], 0
	v_pk_fma_f32 v[180:181], v[180:181], v[180:181], v[182:183]
	s_nop 0
	v_pk_add_f32 v[176:177], v[176:177], v[180:181]
	s_nop 0
	v_add_f32_e32 v114, v176, v177

.LBB0_1429:
	s_and_b64 vcc, exec, s[40:41]
	s_mov_b64 s[82:83], -1
	s_nop 1
	v_mov_b32_e32 v136, v240
	v_mov_b32_e32 v137, v241
	v_mov_b32_e32 v138, v242
	v_mov_b32_e32 v139, v243
	v_lshlrev_b32_e32 v140, 16, v136
	v_and_b32_e32 v141, 0xffff0000, v136
	v_lshlrev_b32_e32 v136, 16, v137
	v_and_b32_e32 v137, 0xffff0000, v137
	v_lshlrev_b32_e32 v178, 16, v138
	v_and_b32_e32 v179, 0xffff0000, v138
	v_lshlrev_b32_e32 v142, 16, v139
	v_and_b32_e32 v143, 0xffff0000, v139
	v_pk_add_f32 v[138:139], v[32:33], v[136:137]
	v_pk_add_f32 v[136:137], v[30:31], v[140:141]
	v_pk_add_f32 v[142:143], v[28:29], v[142:143]
	v_pk_add_f32 v[140:141], v[26:27], v[178:179]
	s_cbranch_vccz .LBB0_1432
	s_andn2_b64 vcc, exec, s[82:83]
	s_cbranch_vccz .LBB0_1433

.LBB0_1437:
	v_add_u32_e32 v172, 0x90, v170
	v_ashrrev_i32_e32 v173, 31, v172
	s_waitcnt lgkmcnt(0)
	v_lshlrev_b64 v[136:137], 13, v[172:173]
	v_lshl_add_u64 v[136:137], s[46:47], 0, v[136:137]
	v_lshl_add_u64 v[178:179], v[116:117], 1, v[136:137]
	s_mov_b64 s[100:101], 0x20000
	global_load_dwordx4 v[184:187], v[178:179], off
	global_load_dwordx4 v[188:191], v[178:179], off offset:256
	v_lshl_add_u64 v[196:197], v[178:179], 0, s[100:101]
	global_load_dwordx4 v[192:195], v[196:197], off
	global_load_dwordx4 v[210:213], v[196:197], off offset:256
	v_lshl_add_u64 v[196:197], v[196:197], 0, s[100:101]
	global_load_dwordx4 v[214:217], v[196:197], off
	global_load_dwordx4 v[218:221], v[196:197], off offset:256
	v_lshlrev_b64 v[174:175], 12, v[172:173]
	s_mov_b64 s[82:83], -1
	s_and_b64 vcc, exec, s[40:41]
	v_lshl_add_u64 v[174:175], v[174:175], 1, s[50:51]
	s_waitcnt vmcnt(0)
	s_nop 1
	v_mov_b32_e32 v136, v184
	v_mov_b32_e32 v137, v185
	v_mov_b32_e32 v138, v186
	v_mov_b32_e32 v139, v187
	v_lshlrev_b32_e32 v140, 16, v136
	v_and_b32_e32 v141, 0xffff0000, v136
	v_lshlrev_b32_e32 v136, 16, v137
	v_and_b32_e32 v137, 0xffff0000, v137
	v_lshlrev_b32_e32 v176, 16, v138
	v_and_b32_e32 v177, 0xffff0000, v138
	v_lshlrev_b32_e32 v142, 16, v139
	v_and_b32_e32 v143, 0xffff0000, v139
	v_pk_add_f32 v[138:139], v[56:57], v[136:137]
	v_pk_add_f32 v[136:137], v[54:55], v[140:141]
	v_pk_add_f32 v[142:143], v[52:53], v[142:143]
	v_pk_add_f32 v[140:141], v[50:51], v[176:177]
	s_cbranch_vccnz .LBB0_1439
	v_cvt_pk_bf16_f32 v180, v136, v137
	v_cvt_pk_bf16_f32 v181, v138, v139
	v_lshl_add_u64 v[176:177], v[116:117], 1, v[174:175]
	v_cvt_pk_bf16_f32 v182, v140, v141
	v_cvt_pk_bf16_f32 v183, v142, v143
	global_store_dwordx4 v[176:177], v[180:183], off
	v_mov_b32_e32 v176, v136
	v_mov_b32_e32 v177, v140
	v_mov_b32_e32 v180, v137
	v_mov_b32_e32 v181, v141
	v_pk_mul_f32 v[180:181], v[180:181], v[180:181]
	v_mov_b32_e32 v182, v139
	v_mov_b32_e32 v183, v143
	v_pk_fma_f32 v[176:177], v[176:177], v[176:177], v[180:181]
	v_mov_b32_e32 v180, v138
	v_mov_b32_e32 v181, v142
	v_pk_mul_f32 v[182:183], v[182:183], v[182:183]
	s_mov_b64 s[82:83], 0
	v_pk_fma_f32 v[180:181], v[180:181], v[180:181], v[182:183]
	s_nop 0
	v_pk_add_f32 v[176:177], v[176:177], v[180:181]
	s_nop 0
	v_add_f32_e32 v114, v176, v177

.LBB0_1441:
	s_and_b64 vcc, exec, s[40:41]
	s_mov_b64 s[82:83], -1
	s_nop 1
	v_mov_b32_e32 v136, v188
	v_mov_b32_e32 v137, v189
	v_mov_b32_e32 v138, v190
	v_mov_b32_e32 v139, v191
	v_lshlrev_b32_e32 v140, 16, v136
	v_and_b32_e32 v141, 0xffff0000, v136
	v_lshlrev_b32_e32 v136, 16, v137
	v_and_b32_e32 v137, 0xffff0000, v137
	v_lshlrev_b32_e32 v178, 16, v138
	v_and_b32_e32 v179, 0xffff0000, v138
	v_lshlrev_b32_e32 v142, 16, v139
	v_and_b32_e32 v143, 0xffff0000, v139
	v_pk_add_f32 v[138:139], v[24:25], v[136:137]
	v_pk_add_f32 v[136:137], v[22:23], v[140:141]
	v_pk_add_f32 v[142:143], v[20:21], v[142:143]
	v_pk_add_f32 v[140:141], v[18:19], v[178:179]
	s_cbranch_vccz .LBB0_1444
	s_andn2_b64 vcc, exec, s[82:83]
	s_cbranch_vccz .LBB0_1445

.LBB0_1449:
	v_add_u32_e32 v172, 0xa0, v170
	v_ashrrev_i32_e32 v173, 31, v172
	s_waitcnt lgkmcnt(0)
	v_lshlrev_b64 v[136:137], 13, v[172:173]
	v_lshl_add_u64 v[136:137], s[46:47], 0, v[136:137]
	v_lshl_add_u64 v[178:179], v[116:117], 1, v[136:137]
	v_lshlrev_b64 v[174:175], 12, v[172:173]
	s_mov_b64 s[82:83], -1
	s_and_b64 vcc, exec, s[40:41]
	v_lshl_add_u64 v[174:175], v[174:175], 1, s[50:51]
	s_nop 1
	v_mov_b32_e32 v136, v192
	v_mov_b32_e32 v137, v193
	v_mov_b32_e32 v138, v194
	v_mov_b32_e32 v139, v195
	v_lshlrev_b32_e32 v140, 16, v136
	v_and_b32_e32 v141, 0xffff0000, v136
	v_lshlrev_b32_e32 v136, 16, v137
	v_and_b32_e32 v137, 0xffff0000, v137
	v_lshlrev_b32_e32 v176, 16, v138
	v_and_b32_e32 v177, 0xffff0000, v138
	v_lshlrev_b32_e32 v142, 16, v139
	v_and_b32_e32 v143, 0xffff0000, v139
	v_pk_add_f32 v[138:139], v[48:49], v[136:137]
	v_pk_add_f32 v[136:137], v[46:47], v[140:141]
	v_pk_add_f32 v[142:143], v[44:45], v[142:143]
	v_pk_add_f32 v[140:141], v[42:43], v[176:177]
	s_cbranch_vccnz .LBB0_1451
	v_cvt_pk_bf16_f32 v180, v136, v137
	v_cvt_pk_bf16_f32 v181, v138, v139
	v_lshl_add_u64 v[176:177], v[116:117], 1, v[174:175]
	v_cvt_pk_bf16_f32 v182, v140, v141
	v_cvt_pk_bf16_f32 v183, v142, v143
	global_store_dwordx4 v[176:177], v[180:183], off
	v_mov_b32_e32 v176, v136
	v_mov_b32_e32 v177, v140
	v_mov_b32_e32 v180, v137
	v_mov_b32_e32 v181, v141
	v_pk_mul_f32 v[180:181], v[180:181], v[180:181]
	v_mov_b32_e32 v182, v139
	v_mov_b32_e32 v183, v143
	v_pk_fma_f32 v[176:177], v[176:177], v[176:177], v[180:181]
	v_mov_b32_e32 v180, v138
	v_mov_b32_e32 v181, v142
	v_pk_mul_f32 v[182:183], v[182:183], v[182:183]
	s_mov_b64 s[82:83], 0
	v_pk_fma_f32 v[180:181], v[180:181], v[180:181], v[182:183]
	s_nop 0
	v_pk_add_f32 v[176:177], v[176:177], v[180:181]
	s_nop 0
	v_add_f32_e32 v114, v176, v177

.LBB0_1453:
	s_and_b64 vcc, exec, s[40:41]
	s_mov_b64 s[82:83], -1
	s_nop 1
	v_mov_b32_e32 v136, v210
	v_mov_b32_e32 v137, v211
	v_mov_b32_e32 v138, v212
	v_mov_b32_e32 v139, v213
	v_lshlrev_b32_e32 v140, 16, v136
	v_and_b32_e32 v141, 0xffff0000, v136
	v_lshlrev_b32_e32 v136, 16, v137
	v_and_b32_e32 v137, 0xffff0000, v137
	v_lshlrev_b32_e32 v178, 16, v138
	v_and_b32_e32 v179, 0xffff0000, v138
	v_lshlrev_b32_e32 v142, 16, v139
	v_and_b32_e32 v143, 0xffff0000, v139
	v_pk_add_f32 v[138:139], v[16:17], v[136:137]
	v_pk_add_f32 v[136:137], v[14:15], v[140:141]
	v_pk_add_f32 v[142:143], v[12:13], v[142:143]
	v_pk_add_f32 v[140:141], v[10:11], v[178:179]
	s_cbranch_vccz .LBB0_1456
	s_andn2_b64 vcc, exec, s[82:83]
	s_cbranch_vccz .LBB0_1457

.LBB0_1461:
	v_add_u32_e32 v170, 0xb0, v170
	v_ashrrev_i32_e32 v171, 31, v170
	s_waitcnt lgkmcnt(0)
	v_lshlrev_b64 v[136:137], 13, v[170:171]
	v_lshl_add_u64 v[136:137], s[46:47], 0, v[136:137]
	v_lshl_add_u64 v[176:177], v[116:117], 1, v[136:137]
	v_lshlrev_b64 v[172:173], 12, v[170:171]
	s_mov_b64 s[82:83], -1
	s_and_b64 vcc, exec, s[40:41]
	v_lshl_add_u64 v[172:173], v[172:173], 1, s[50:51]
	s_nop 1
	v_mov_b32_e32 v136, v214
	v_mov_b32_e32 v137, v215
	v_mov_b32_e32 v138, v216
	v_mov_b32_e32 v139, v217
	v_lshlrev_b32_e32 v140, 16, v136
	v_and_b32_e32 v141, 0xffff0000, v136
	v_lshlrev_b32_e32 v136, 16, v137
	v_and_b32_e32 v137, 0xffff0000, v137
	v_lshlrev_b32_e32 v174, 16, v138
	v_and_b32_e32 v175, 0xffff0000, v138
	v_lshlrev_b32_e32 v142, 16, v139
	v_and_b32_e32 v143, 0xffff0000, v139
	v_pk_add_f32 v[138:139], v[40:41], v[136:137]
	v_pk_add_f32 v[136:137], v[38:39], v[140:141]
	v_pk_add_f32 v[142:143], v[36:37], v[142:143]
	v_pk_add_f32 v[140:141], v[34:35], v[174:175]
	s_cbranch_vccnz .LBB0_1463
	v_cvt_pk_bf16_f32 v178, v136, v137
	v_cvt_pk_bf16_f32 v179, v138, v139
	v_lshl_add_u64 v[174:175], v[116:117], 1, v[172:173]
	v_cvt_pk_bf16_f32 v180, v140, v141
	v_cvt_pk_bf16_f32 v181, v142, v143
	global_store_dwordx4 v[174:175], v[178:181], off
	v_mov_b32_e32 v174, v136
	v_mov_b32_e32 v175, v140
	v_mov_b32_e32 v178, v137
	v_mov_b32_e32 v179, v141
	v_pk_mul_f32 v[178:179], v[178:179], v[178:179]
	v_mov_b32_e32 v180, v139
	v_mov_b32_e32 v181, v143
	v_pk_fma_f32 v[174:175], v[174:175], v[174:175], v[178:179]
	v_mov_b32_e32 v178, v138
	v_mov_b32_e32 v179, v142
	v_pk_mul_f32 v[180:181], v[180:181], v[180:181]
	s_mov_b64 s[82:83], 0
	v_pk_fma_f32 v[178:179], v[178:179], v[178:179], v[180:181]
	s_nop 0
	v_pk_add_f32 v[174:175], v[174:175], v[178:179]
	s_nop 0
	v_add_f32_e32 v114, v174, v175

.LBB0_1465:
	s_and_b64 vcc, exec, s[40:41]
	s_mov_b64 s[82:83], -1
	s_nop 1
	v_mov_b32_e32 v136, v218
	v_mov_b32_e32 v137, v219
	v_mov_b32_e32 v138, v220
	v_mov_b32_e32 v139, v221
	v_lshlrev_b32_e32 v140, 16, v136
	v_and_b32_e32 v141, 0xffff0000, v136
	v_lshlrev_b32_e32 v136, 16, v137
	v_and_b32_e32 v137, 0xffff0000, v137
	v_lshlrev_b32_e32 v176, 16, v138
	v_and_b32_e32 v177, 0xffff0000, v138
	v_lshlrev_b32_e32 v142, 16, v139
	v_and_b32_e32 v143, 0xffff0000, v139
	v_pk_add_f32 v[138:139], v[8:9], v[136:137]
	v_pk_add_f32 v[136:137], v[6:7], v[140:141]
	v_pk_add_f32 v[142:143], v[4:5], v[142:143]
	v_pk_add_f32 v[140:141], v[2:3], v[176:177]
	s_cbranch_vccz .LBB0_1468
	s_andn2_b64 vcc, exec, s[82:83]
	s_cbranch_vccz .LBB0_1469
